# fox2-negated-aux
# speedup vs baseline: 1.0107x; 1.0031x over previous
; __device__ __forceinline__ void fox2_phase(LAS unsigned char* lds, const bf16_t* QKV, const float* CL2, bf16_t* AO) {
;     ...
;         v4u kr = ld_tile(Kg, 0, 64, tid), vr = ld_tile(Vg, 0, 64, tid); float ar = (tid < 64) ? cl[tid] : 0.f;
;         v4u kr2 = ld_tile(Kg, 64, 64, tid), vr2 = ld_tile(Vg, 64, 64, tid); float ar2 = (tid < 64) ? cl[64 + tid] : 0.f;
;         __syncthreads();
;         st_k(lds + ATT_K, kr, tid); st_v(lds + ATT_V, vr, tid); if (tid < 64) AUXL[tid] = ar;
;         st_k(lds + ATT_K + KTB, kr2, tid); st_v(lds + ATT_V + VTB, vr2, tid); if (tid < 64) AUXL[64 + tid] = ar2;
;         kr = ld_tile(Kg, 128, 64, tid); vr = ld_tile(Vg, 128, 64, tid); if (tid < 64) ar = cl[128 + tid];
.LBB0_209:
	s_or_saveexec_b64 s[6:7], s[6:7]
	v_lshl_add_u32 v247, v66, 2, 0
	s_xor_b64 exec, exec, s[6:7]
	s_cbranch_execz .LBB0_211
	v_xor_b32_e32 v223, 0x80000000, v223
	ds_write_b32 v247, v223 offset:52608
	s_waitcnt vmcnt(1)
	ds_write_b128 v244, v[6:9] offset:9216
	s_waitcnt vmcnt(0)
	ds_write_b128 v245, v[10:13] offset:35968
	v_xor_b32_e32 v18, 0x80000000, v18
	ds_write_b32 v247, v18 offset:52864

; __device__ __forceinline__ void fox2_phase(LAS unsigned char* lds, const bf16_t* QKV, const float* CL2, bf16_t* AO) {
;     ...
;             __syncthreads();
;             const int b2 = (bi >= 1) ? bi - 1 : 2;
;             if (t + 2 < nt) { st_k(lds + ATT_K + b2 * KTB, kr, tid); st_v(lds + ATT_V + b2 * VTB, vr, tid); if (tid < 64) AUXL[b2 * 64 + tid] = ar;
;                 if (t + 3 < nt) { kr = ld_tile(Kg, 64 * (t + 3), 64, tid); vr = ld_tile(Vg, 64 * (t + 3), 64, tid); if (tid < 64) ar = cl[64 * (t + 3) + tid]; } }
.LBB0_217:
	s_add_i32 s60, s72, 2
	s_cmp_ge_u32 s60, s65
	s_waitcnt lgkmcnt(0)
	s_barrier
	s_cbranch_scc1 .LBB0_224
	s_add_i32 s60, s73, -1
	s_cmp_gt_i32 s73, 0
	s_cselect_b32 s60, s60, 2
	s_mul_i32 s61, s60, 0x2400
	v_add_u32_e32 v66, s61, v244
	s_mul_i32 s61, s60, 0x2080
	s_waitcnt vmcnt(1)
	ds_write_b128 v66, v[162:165]
	v_add_u32_e32 v66, s61, v245
	s_waitcnt vmcnt(0)
	ds_write_b128 v66, v[166:169] offset:27648
	s_and_saveexec_b64 vcc, s[40:41]
	v_lshl_add_u32 v66, s60, 8, v247
	v_xor_b32_e32 v223, 0x80000000, v223
	ds_write_b32 v66, v223 offset:52608
	s_or_b64 exec, exec, vcc
	s_add_i32 s60, s72, 3
	s_cmp_ge_u32 s60, s65
	s_cbranch_scc1 .LBB0_237
	v_ashrrev_i32_e32 v225, 31, v224
	v_lshlrev_b64 v[66:67], 7, v[224:225]
	v_lshl_add_u64 v[68:69], v[218:219], 0, v[66:67]
	v_lshl_add_u64 v[66:67], v[220:221], 0, v[66:67]
	global_load_dwordx4 v[162:165], v[68:69], off
	global_load_dwordx4 v[166:169], v[66:67], off
	s_and_saveexec_b64 vcc, s[40:41]
	s_mov_b32 s76, 0xff800000
	s_cbranch_execz .LBB0_223
	v_ashrrev_i32_e32 v223, 31, v222
	v_lshl_add_u64 v[66:67], v[222:223], 2, s[56:57]
	global_load_dword v223, v[66:67], off

; #define LAS __attribute__((address_space(3)))
; __device__ __forceinline__ int crow(int r, int hi) { return (r & 3) + 8 * (r >> 2) + 4 * hi; }
; __device__ __forceinline__ void fox_scores(v16f& p0, v16f& p1, const v16f& c0, const v16f& c1, bool diag, int t, int qpos, int hi) {
;     p0 = p0 * C1 - c0; p1 = p1 * C1 - c1;
;     if (diag) {
; #pragma unroll
;         for (int r = 0; r < 16; ++r) { const int kv = 64 * t + crow(r, hi); if (kv > qpos) p0[r] = -INFINITY; if (kv + 32 > qpos) p1[r] = -INFINITY; }
;     }
; }
; __device__ __forceinline__ void fox2_phase(LAS unsigned char* lds, const bf16_t* QKV, const float* CL2, bf16_t* AO) {
;     ...
;             if (t <= tw) {
;                 const bool diag = (t == tw);
;                 v16f a0, a1, b0, b1;
;                 { v8s kf[8]; k_load(lds + ATT_K + bi * KTB, kf, r32, hi); qk_mma(kf, qa, a0, a1); qk_mma(kf, qb_, b0, b1); }
;                 { v16f c0, c1; const LAS float* kbp = AUXL + bi * 64 + 4 * hi;
; #pragma unroll
;                   for (int g = 0; g < 4; ++g) { const v4f x0 = *(const LAS v4f*)(kbp + 8 * g), x1 = *(const LAS v4f*)(kbp + 32 + 8 * g);
; #pragma unroll
;                       for (int e = 0; e < 4; ++e) { c0[4 * g + e] = x0[e]; c1[4 * g + e] = x1[e]; } }
;                   fox_scores(a0, a1, c0, c1, diag, t, qposA, hi); fox_scores(b0, b1, c0, c1, diag, t, qposB, hi); }
.LBB0_225:
	s_mul_i32 s60, s73, 0x2400
	v_add_u32_e32 v70, s60, v249
	ds_read_b128 v[82:85], v70 offset:4608
	ds_read_b128 v[66:69], v70
	ds_read_b128 v[86:89], v70 offset:32
	ds_read_b128 v[226:229], v70 offset:4640
	ds_read_b128 v[90:93], v70 offset:64
	ds_read_b128 v[230:233], v70 offset:4672
	ds_read_b128 v[94:97], v70 offset:96
	ds_read_b128 v[204:207], v70 offset:4704
	s_waitcnt lgkmcnt(6)
	v_mfma_f32_32x32x16_bf16 v[98:113], v[66:69], v[130:133], 0
	s_cmp_eq_u32 s68, s72
	s_cselect_b64 vcc, -1, 0
	s_cmp_lg_u32 s68, s72
	v_mfma_f32_32x32x16_bf16 v[66:81], v[66:69], v[138:141], 0
	s_waitcnt lgkmcnt(5)
	v_mfma_f32_32x32x16_bf16 v[98:113], v[86:89], v[134:137], v[98:113]
	v_mfma_f32_32x32x16_bf16 v[66:81], v[86:89], v[142:145], v[66:81]
	v_lshl_add_u32 v86, s73, 8, v248
	ds_read_b128 v[170:173], v86 offset:52736
	ds_read_b128 v[186:189], v86 offset:52608
	ds_read_b128 v[190:193], v86 offset:52640
	ds_read_b128 v[174:177], v86 offset:52768
	ds_read_b128 v[194:197], v86 offset:52672
	ds_read_b128 v[178:181], v86 offset:52800
	ds_read_b128 v[198:201], v86 offset:52704
	ds_read_b128 v[182:185], v86 offset:52832
	s_waitcnt lgkmcnt(5)
	s_waitcnt lgkmcnt(3)
	s_waitcnt lgkmcnt(1)
	v_mfma_f32_32x32x16_bf16 v[98:113], v[90:93], v[146:149], v[98:113]
	v_mfma_f32_32x32x16_bf16 v[66:81], v[90:93], v[154:157], v[66:81]
	v_mfma_f32_32x32x16_bf16 v[114:129], v[82:85], v[130:133], 0
	v_mfma_f32_32x32x16_bf16 v[98:113], v[94:97], v[150:153], v[98:113]
	v_mfma_f32_32x32x16_bf16 v[66:81], v[94:97], v[158:161], v[66:81]
	s_nop 10
	v_fma_f32 v112, v112, s52, v200
	v_fma_f32 v113, v113, s52, v201
	v_fma_f32 v108, v108, s52, v196
	v_fma_f32 v109, v109, s52, v197
	v_fma_f32 v104, v104, s52, v192
	v_fma_f32 v105, v105, s52, v193
	v_pk_fma_f32 v[100:101], v[100:101], s[52:53], v[188:189] op_sel_hi:[1,0,1]
	v_pk_fma_f32 v[98:99], v[98:99], s[52:53], v[186:187] op_sel_hi:[1,0,1]
	v_pk_fma_f32 v[110:111], v[110:111], s[52:53], v[198:199] op_sel_hi:[1,0,1]
	v_pk_fma_f32 v[106:107], v[106:107], s[52:53], v[194:195] op_sel_hi:[1,0,1]
	v_mfma_f32_32x32x16_bf16 v[82:97], v[82:85], v[138:141], 0
	v_fma_f32 v102, v102, s52, v190
	v_fma_f32 v103, v103, s52, v191
	v_mfma_f32_32x32x16_bf16 v[114:129], v[226:229], v[134:137], v[114:129]
	v_mfma_f32_32x32x16_bf16 v[82:97], v[226:229], v[142:145], v[82:97]
	v_mov_b32_e32 v227, v177
	v_mov_b32_e32 v226, v176
	v_mov_b32_e32 v229, v173
	v_mov_b32_e32 v228, v172
	v_mfma_f32_32x32x16_bf16 v[114:129], v[230:233], v[146:149], v[114:129]
	v_mfma_f32_32x32x16_bf16 v[82:97], v[230:233], v[154:157], v[82:97]
	s_waitcnt lgkmcnt(0)
	v_mov_b32_e32 v231, v185
	v_mov_b32_e32 v230, v184
	v_mov_b32_e32 v233, v181
	v_mov_b32_e32 v232, v180
	v_mfma_f32_32x32x16_bf16 v[114:129], v[204:207], v[150:153], v[114:129]
	v_mfma_f32_32x32x16_bf16 v[82:97], v[204:207], v[158:161], v[82:97]
	s_nop 10
	v_fma_f32 v128, v128, s52, v184
	v_fma_f32 v129, v129, s52, v185
	v_fma_f32 v124, v124, s52, v180
	v_fma_f32 v125, v125, s52, v181
	v_fma_f32 v120, v120, s52, v176
	v_fma_f32 v121, v121, s52, v177
	v_pk_fma_f32 v[116:117], v[116:117], s[52:53], v[172:173] op_sel_hi:[1,0,1]
	v_pk_fma_f32 v[114:115], v[114:115], s[52:53], v[170:171] op_sel_hi:[1,0,1]
	v_pk_fma_f32 v[126:127], v[126:127], s[52:53], v[182:183] op_sel_hi:[1,0,1]
	v_pk_fma_f32 v[122:123], v[122:123], s[52:53], v[178:179] op_sel_hi:[1,0,1]
	v_pk_fma_f32 v[118:119], v[118:119], s[52:53], v[174:175] op_sel_hi:[1,0,1]
	s_cbranch_scc1 .LBB0_229
	v_readlane_b32 s60, v255, 19
	v_readlane_b32 s61, v255, 20
	v_cndmask_b32_e64 v124, v124, v241, s[84:85]
	v_cndmask_b32_e64 v125, v125, v241, s[88:89]
	v_cndmask_b32_e64 v114, v114, v241, s[60:61]
	v_readlane_b32 s60, v255, 21
	v_readlane_b32 s61, v255, 22
	v_cndmask_b32_e64 v126, v126, v241, s[92:93]
	v_cndmask_b32_e64 v127, v127, v241, s[96:97]
	v_cndmask_b32_e64 v115, v115, v241, s[60:61]
	v_readlane_b32 s60, v255, 23
	v_readlane_b32 s61, v255, 24
	v_cndmask_b32_e64 v128, v128, v241, s[6:7]
	s_nop 0
	v_cndmask_b32_e64 v116, v116, v241, s[60:61]
	v_readlane_b32 s60, v255, 25
	v_readlane_b32 s61, v255, 26
	s_nop 1
	v_cndmask_b32_e64 v117, v117, v241, s[60:61]
	v_readlane_b32 s60, v255, 27
	v_readlane_b32 s61, v255, 28
	s_nop 1
	v_cndmask_b32_e64 v118, v118, v241, s[60:61]
	v_readlane_b32 s60, v255, 29
	v_readlane_b32 s61, v255, 30
	s_nop 1
	v_cndmask_b32_e64 v119, v119, v241, s[60:61]
	v_readlane_b32 s60, v255, 31
	v_readlane_b32 s61, v255, 32
	s_nop 1
	v_cndmask_b32_e64 v120, v120, v241, s[60:61]
	v_readlane_b32 s60, v255, 33
	v_readlane_b32 s61, v255, 34
	s_nop 1
	v_cndmask_b32_e64 v121, v121, v241, s[60:61]
	v_readlane_b32 s60, v255, 35
	v_readlane_b32 s61, v255, 36
	s_nop 1
	v_cndmask_b32_e64 v122, v122, v241, s[60:61]
	v_readlane_b32 s60, v255, 37
	v_readlane_b32 s61, v255, 38
	s_nop 1
	v_cndmask_b32_e64 v123, v123, v241, s[60:61]
	s_and_saveexec_b64 s[60:61], s[10:11]
	v_mov_b32_e32 v129, s80
	s_or_b64 exec, exec, s[60:61]
	v_cndmask_b32_e64 v172, v98, v241, s[42:43]
	v_cndmask_b32_e64 v99, v241, v99, s[46:47]
	v_cndmask_b32_e64 v98, v172, v98, s[46:47]
	v_cndmask_b32_e64 v100, v100, v241, s[50:51]
	v_cndmask_b32_e64 v101, v101, v241, s[54:55]
	v_cndmask_b32_e64 v102, v102, v241, s[58:59]
	v_cndmask_b32_e64 v103, v103, v241, s[62:63]
	v_cndmask_b32_e64 v104, v104, v241, s[66:67]
	v_cndmask_b32_e64 v105, v105, v241, s[70:71]
	v_cndmask_b32_e64 v106, v106, v241, s[74:75]
	v_cndmask_b32_e64 v107, v107, v241, s[78:79]
	v_cndmask_b32_e64 v108, v108, v241, s[82:83]
	v_cndmask_b32_e64 v109, v109, v241, s[86:87]
	v_cndmask_b32_e64 v110, v110, v241, s[90:91]
	v_cndmask_b32_e64 v111, v111, v241, s[94:95]
	v_cndmask_b32_e64 v112, v112, v241, s[4:5]
	v_cndmask_b32_e64 v113, v113, v241, s[8:9]
; __device__ __forceinline__ int crow(int r, int hi) { return (r & 3) + 8 * (r >> 2) + 4 * hi; }
; __device__ __forceinline__ void fox_scores(v16f& p0, v16f& p1, const v16f& c0, const v16f& c1, bool diag, int t, int qpos, int hi) {
;     p0 = p0 * C1 - c0; p1 = p1 * C1 - c1;
;     if (diag) {
; #pragma unroll
;         for (int r = 0; r < 16; ++r) { const int kv = 64 * t + crow(r, hi); if (kv > qpos) p0[r] = -INFINITY; if (kv + 32 > qpos) p1[r] = -INFINITY; }
;     }
; }
.LBB0_229:
	v_pk_fma_f32 v[176:177], v[66:67], s[52:53], v[186:187] op_sel_hi:[1,0,1]
	v_pk_fma_f32 v[78:79], v[78:79], s[52:53], v[198:199] op_sel_hi:[1,0,1]
	v_pk_fma_f32 v[94:95], v[94:95], s[52:53], v[182:183] op_sel_hi:[1,0,1]
	v_pk_fma_f32 v[74:75], v[74:75], s[52:53], v[194:195] op_sel_hi:[1,0,1]
	v_pk_fma_f32 v[172:173], v[72:73], s[52:53], v[192:193] op_sel_hi:[1,0,1]
	v_pk_fma_f32 v[90:91], v[90:91], s[52:53], v[178:179] op_sel_hi:[1,0,1]
	v_pk_fma_f32 v[80:81], v[80:81], s[52:53], v[200:201] op_sel_hi:[1,0,1]
	v_pk_fma_f32 v[76:77], v[76:77], s[52:53], v[196:197] op_sel_hi:[1,0,1]
	v_pk_fma_f32 v[180:181], v[70:71], s[52:53], v[190:191] op_sel_hi:[1,0,1]
	v_pk_fma_f32 v[184:185], v[68:69], s[52:53], v[188:189] op_sel_hi:[1,0,1]
	v_pk_fma_f32 v[96:97], v[96:97], s[52:53], v[230:231] op_sel_hi:[1,0,1]
	v_pk_fma_f32 v[92:93], v[92:93], s[52:53], v[232:233] op_sel_hi:[1,0,1]
	v_pk_fma_f32 v[70:71], v[88:89], s[52:53], v[226:227] op_sel_hi:[1,0,1]
	v_pk_fma_f32 v[72:73], v[86:87], s[52:53], v[174:175] op_sel_hi:[1,0,1]
	v_pk_fma_f32 v[66:67], v[84:85], s[52:53], v[228:229] op_sel_hi:[1,0,1]
	s_andn2_b64 vcc, exec, vcc
	v_pk_fma_f32 v[68:69], v[82:83], s[52:53], v[170:171] op_sel_hi:[1,0,1]
	s_cbranch_vccnz .LBB0_233
	v_cndmask_b32_e64 v82, v68, v241, s[42:43]
	v_cndmask_b32_e64 v69, v241, v69, s[46:47]
	v_cndmask_b32_e64 v68, v82, v68, s[46:47]
	v_cndmask_b32_e64 v66, v66, v241, s[50:51]
	v_cndmask_b32_e64 v67, v67, v241, s[54:55]
	v_cndmask_b32_e64 v72, v72, v241, s[58:59]
	v_cndmask_b32_e64 v73, v73, v241, s[62:63]
	v_cndmask_b32_e64 v70, v70, v241, s[66:67]
	v_cndmask_b32_e64 v71, v71, v241, s[70:71]
	v_cndmask_b32_e64 v90, v90, v241, s[74:75]
	v_cndmask_b32_e64 v91, v91, v241, s[78:79]
	v_cndmask_b32_e64 v92, v92, v241, s[82:83]
	v_cndmask_b32_e64 v93, v93, v241, s[86:87]
	v_cndmask_b32_e64 v94, v94, v241, s[90:91]
	v_cndmask_b32_e64 v95, v95, v241, s[94:95]
	v_cndmask_b32_e64 v96, v96, v241, s[4:5]
	s_and_saveexec_b64 s[60:61], s[8:9]
	v_mov_b32_e32 v97, s80
	s_or_b64 exec, exec, s[60:61]
	v_cndmask_b32_e64 v82, v176, v241, s[12:13]
	v_cndmask_b32_e64 v177, v241, v177, s[14:15]
	v_cndmask_b32_e64 v176, v82, v176, s[14:15]
	v_cndmask_b32_e64 v184, v184, v241, s[16:17]
	v_cndmask_b32_e64 v185, v185, v241, s[18:19]
	v_cndmask_b32_e64 v180, v180, v241, s[20:21]
	v_cndmask_b32_e64 v181, v181, v241, s[22:23]
	v_cndmask_b32_e64 v172, v172, v241, s[24:25]
	v_cndmask_b32_e64 v173, v173, v241, s[26:27]
	v_cndmask_b32_e64 v74, v74, v241, s[28:29]
	v_cndmask_b32_e64 v75, v75, v241, s[30:31]
	v_cndmask_b32_e64 v76, v76, v241, s[34:35]
	v_cndmask_b32_e64 v77, v77, v241, s[36:37]
	v_cndmask_b32_e64 v78, v78, v241, s[48:49]
	v_cndmask_b32_e64 v79, v79, v241, s[38:39]
	v_cndmask_b32_e64 v80, v80, v241, s[44:45]
	v_cndmask_b32_e64 v81, v81, v241, s[0:1]
